# baseline (speedup 1.0000x reference)
.LBB0_848:
	s_lshl_b32 s22, s35, 8
	v_add_u32_e32 v130, s22, v208
	s_cmp_lt_i32 s34, 4
	v_and_b32_e32 v136, 0x3f8f, v130
	s_mov_b64 s[18:19], -1
	s_cbranch_scc1 .LBB0_851
	v_ashrrev_i32_e32 v131, 31, v130
	v_lshlrev_b64 v[132:133], 8, v[130:131]
	v_ashrrev_i32_e32 v131, 11, v130
	v_lshl_add_u64 v[134:135], v[194:195], 0, v[132:133]
	v_and_b32_e32 v132, -8, v131
	v_lshl_add_u32 v131, s34, 2, v209
	v_add_u32_e32 v132, v132, v131
	v_ashrrev_i32_e32 v133, 31, v132
	v_lshlrev_b64 v[138:139], 14, v[132:133]
	v_or_b32_e32 v132, v138, v136
	s_movk_i32 s2, 0x180
	v_mad_u64_u32 v[132:133], s[18:19], v132, s2, v[196:197]
	v_mad_i32_i24 v133, v139, s2, v133
	global_load_dwordx4 v[158:161], v[134:135], off
	global_load_dwordx4 v[162:165], v[134:135], off offset:16
	global_load_dwordx4 v[166:169], v[134:135], off offset:128
	global_load_dwordx4 v[170:173], v[134:135], off offset:144
	v_mov_b32_e32 v142, v126
	v_mov_b32_e32 v143, v118
	v_mov_b32_e32 v148, v128
	v_mov_b32_e32 v149, v120
	s_waitcnt vmcnt(3)
	v_pk_mul_f32 v[142:143], v[142:143], v[158:159]
	s_nop 0
	v_sub_f32_e32 v137, v142, v143
	v_mov_b32_e32 v142, v127
	v_mov_b32_e32 v143, v119
	v_pk_mul_f32 v[142:143], v[142:143], v[160:161]
	v_mul_f32_e32 v137, 0x3d93cd3a, v137
	v_sub_f32_e32 v142, v142, v143
	v_mul_f32_e32 v142, 0x3d93cd3a, v142
	v_cvt_pk_bf16_f32 v146, v137, v142
	s_waitcnt vmcnt(2)
	v_pk_mul_f32 v[148:149], v[148:149], v[162:163]
	s_nop 0
	v_sub_f32_e32 v137, v148, v149
	v_mov_b32_e32 v148, v129
	v_mov_b32_e32 v149, v121
	v_pk_mul_f32 v[148:149], v[148:149], v[164:165]
	v_mul_f32_e32 v137, 0x3d93cd3a, v137
	v_sub_f32_e32 v147, v148, v149
	v_mul_f32_e32 v147, 0x3d93cd3a, v147
	v_cvt_pk_bf16_f32 v147, v137, v147
	global_store_dwordx2 v[132:133], v[146:147], off offset:256
	v_mov_b32_e32 v146, v118
	v_mov_b32_e32 v147, v126
	v_pk_mul_f32 v[138:139], v[146:147], v[158:159]
	s_nop 0
	v_add_f32_e32 v137, v138, v139
	v_mov_b32_e32 v138, v119
	v_mov_b32_e32 v139, v127
	v_pk_mul_f32 v[138:139], v[138:139], v[160:161]
	v_mov_b32_e32 v140, v120
	v_add_f32_e32 v138, v138, v139
	v_mov_b32_e32 v141, v128
	v_mul_f32_e32 v137, 0x3d93cd3a, v137
	v_mul_f32_e32 v138, 0x3d93cd3a, v138
	v_pk_mul_f32 v[140:141], v[140:141], v[162:163]
	v_cvt_pk_bf16_f32 v138, v137, v138
	v_mov_b32_e32 v142, v122
	v_add_f32_e32 v137, v140, v141
	v_mov_b32_e32 v140, v121
	v_mov_b32_e32 v141, v129
	v_pk_mul_f32 v[140:141], v[140:141], v[164:165]
	v_mul_f32_e32 v137, 0x3d93cd3a, v137
	v_add_f32_e32 v139, v140, v141
	v_mul_f32_e32 v139, 0x3d93cd3a, v139
	v_cvt_pk_bf16_f32 v139, v137, v139
	global_store_dwordx2 v[132:133], v[138:139], off offset:320
	v_mov_b32_e32 v143, v114
	s_waitcnt vmcnt(3)
	v_pk_mul_f32 v[142:143], v[142:143], v[166:167]
	s_nop 0
	v_sub_f32_e32 v137, v142, v143
	v_mov_b32_e32 v142, v123
	v_mov_b32_e32 v143, v115
	v_pk_mul_f32 v[142:143], v[142:143], v[168:169]
	v_mul_f32_e32 v137, 0x3d93cd3a, v137
	v_sub_f32_e32 v142, v142, v143
	v_mul_f32_e32 v142, 0x3d93cd3a, v142
	v_cvt_pk_bf16_f32 v146, v137, v142
	v_mov_b32_e32 v134, v124
	v_mov_b32_e32 v135, v116
	s_waitcnt vmcnt(2)
	v_pk_mul_f32 v[134:135], v[134:135], v[170:171]
	s_nop 0
	v_sub_f32_e32 v134, v134, v135
	v_mul_f32_e32 v137, 0x3d93cd3a, v134
	v_mov_b32_e32 v134, v125
	v_mov_b32_e32 v135, v117
	v_pk_mul_f32 v[134:135], v[134:135], v[172:173]
	s_nop 0
	v_sub_f32_e32 v134, v134, v135
	v_mul_f32_e32 v134, 0x3d93cd3a, v134
	v_cvt_pk_bf16_f32 v147, v137, v134
	v_mov_b32_e32 v134, v114
	v_mov_b32_e32 v135, v122
	v_pk_mul_f32 v[134:135], v[134:135], v[166:167]
	v_mov_b32_e32 v138, v116
	v_add_f32_e32 v134, v134, v135
	v_mul_f32_e32 v137, 0x3d93cd3a, v134
	v_mov_b32_e32 v134, v115
	v_mov_b32_e32 v135, v123
	v_mov_b32_e32 v139, v124
	v_pk_mul_f32 v[134:135], v[134:135], v[168:169]
	v_pk_mul_f32 v[138:139], v[138:139], v[170:171]
	v_add_f32_e32 v134, v134, v135
	v_add_f32_e32 v135, v138, v139
	v_mov_b32_e32 v138, v117
	v_mov_b32_e32 v139, v125
	v_mul_f32_e32 v134, 0x3d93cd3a, v134
	v_pk_mul_f32 v[138:139], v[138:139], v[172:173]
	v_cvt_pk_bf16_f32 v134, v137, v134
	v_mul_f32_e32 v135, 0x3d93cd3a, v135
	v_add_f32_e32 v137, v138, v139
	global_store_dwordx2 v[132:133], v[146:147], off offset:288
	v_mul_f32_e32 v137, 0x3d93cd3a, v137
	v_cvt_pk_bf16_f32 v135, v135, v137
	global_store_dwordx2 v[132:133], v[134:135], off offset:352
	v_add_u32_e32 v132, s22, v210
	v_ashrrev_i32_e32 v133, 31, v132
	v_lshlrev_b64 v[134:135], 8, v[132:133]
	v_ashrrev_i32_e32 v133, 11, v132
	v_and_b32_e32 v133, -8, v133
	v_add_u32_e32 v138, v133, v131
	v_ashrrev_i32_e32 v139, 31, v138
	v_lshlrev_b64 v[138:139], 14, v[138:139]
	s_movk_i32 s18, 0x3f9f
	v_and_or_b32 v132, v132, s18, v138
	v_lshl_add_u64 v[134:135], v[194:195], 0, v[134:135]
	v_mad_u64_u32 v[132:133], s[18:19], v132, s2, v[196:197]
	v_mad_i32_i24 v133, v139, s2, v133
	global_load_dwordx4 v[158:161], v[134:135], off
	global_load_dwordx4 v[162:165], v[134:135], off offset:16
	global_load_dwordx4 v[166:169], v[134:135], off offset:128
	global_load_dwordx4 v[170:173], v[134:135], off offset:144
	v_mov_b32_e32 v142, v110
	v_mov_b32_e32 v143, v102
	v_mov_b32_e32 v148, v112
	v_mov_b32_e32 v149, v104
	s_waitcnt vmcnt(3)
	v_pk_mul_f32 v[142:143], v[142:143], v[158:159]
	s_nop 0
	v_sub_f32_e32 v137, v142, v143
	v_mov_b32_e32 v142, v111
	v_mov_b32_e32 v143, v103
	v_pk_mul_f32 v[142:143], v[142:143], v[160:161]
	v_mul_f32_e32 v137, 0x3d93cd3a, v137
	v_sub_f32_e32 v142, v142, v143
	v_mul_f32_e32 v142, 0x3d93cd3a, v142
	v_cvt_pk_bf16_f32 v146, v137, v142
	s_waitcnt vmcnt(2)
	v_pk_mul_f32 v[148:149], v[148:149], v[162:163]
	s_nop 0
	v_sub_f32_e32 v137, v148, v149
	v_mov_b32_e32 v148, v113
	v_mov_b32_e32 v149, v105
	v_pk_mul_f32 v[148:149], v[148:149], v[164:165]
	v_mul_f32_e32 v137, 0x3d93cd3a, v137
	v_sub_f32_e32 v147, v148, v149
	v_mul_f32_e32 v147, 0x3d93cd3a, v147
	v_cvt_pk_bf16_f32 v147, v137, v147
	global_store_dwordx2 v[132:133], v[146:147], off offset:256
	v_mov_b32_e32 v146, v102
	v_mov_b32_e32 v147, v110
	v_pk_mul_f32 v[138:139], v[146:147], v[158:159]
	s_nop 0
	v_add_f32_e32 v137, v138, v139
	v_mov_b32_e32 v138, v103
	v_mov_b32_e32 v139, v111
	v_pk_mul_f32 v[138:139], v[138:139], v[160:161]
	v_mov_b32_e32 v140, v104
	v_add_f32_e32 v138, v138, v139
	v_mov_b32_e32 v141, v112
	v_mul_f32_e32 v137, 0x3d93cd3a, v137
	v_mul_f32_e32 v138, 0x3d93cd3a, v138
	v_pk_mul_f32 v[140:141], v[140:141], v[162:163]
	v_cvt_pk_bf16_f32 v138, v137, v138
	v_mov_b32_e32 v142, v106
	v_add_f32_e32 v137, v140, v141
	v_mov_b32_e32 v140, v105
	v_mov_b32_e32 v141, v113
	v_pk_mul_f32 v[140:141], v[140:141], v[164:165]
	v_mul_f32_e32 v137, 0x3d93cd3a, v137
	v_add_f32_e32 v139, v140, v141
	v_mul_f32_e32 v139, 0x3d93cd3a, v139
	v_cvt_pk_bf16_f32 v139, v137, v139
	global_store_dwordx2 v[132:133], v[138:139], off offset:320
	v_mov_b32_e32 v143, v98
	s_waitcnt vmcnt(3)
	v_pk_mul_f32 v[142:143], v[142:143], v[166:167]
	s_nop 0
	v_sub_f32_e32 v137, v142, v143
	v_mov_b32_e32 v142, v107
	v_mov_b32_e32 v143, v99
	v_pk_mul_f32 v[142:143], v[142:143], v[168:169]
	v_mul_f32_e32 v137, 0x3d93cd3a, v137
	v_sub_f32_e32 v142, v142, v143
	v_mul_f32_e32 v142, 0x3d93cd3a, v142
	v_cvt_pk_bf16_f32 v146, v137, v142
	v_mov_b32_e32 v134, v108
	v_mov_b32_e32 v135, v100
	s_waitcnt vmcnt(2)
	v_pk_mul_f32 v[134:135], v[134:135], v[170:171]
	s_nop 0
	v_sub_f32_e32 v134, v134, v135
	v_mul_f32_e32 v137, 0x3d93cd3a, v134
	v_mov_b32_e32 v134, v109
	v_mov_b32_e32 v135, v101
	v_pk_mul_f32 v[134:135], v[134:135], v[172:173]
	s_nop 0
	v_sub_f32_e32 v134, v134, v135
	v_mul_f32_e32 v134, 0x3d93cd3a, v134
	v_cvt_pk_bf16_f32 v147, v137, v134
	v_mov_b32_e32 v134, v98
	v_mov_b32_e32 v135, v106
	v_pk_mul_f32 v[134:135], v[134:135], v[166:167]
	v_mov_b32_e32 v138, v100
	v_add_f32_e32 v134, v134, v135
	v_mul_f32_e32 v137, 0x3d93cd3a, v134
	v_mov_b32_e32 v134, v99
	v_mov_b32_e32 v135, v107
	v_mov_b32_e32 v139, v108
	v_pk_mul_f32 v[134:135], v[134:135], v[168:169]
	v_pk_mul_f32 v[138:139], v[138:139], v[170:171]
	v_add_f32_e32 v134, v134, v135
	v_add_f32_e32 v135, v138, v139
	v_mov_b32_e32 v138, v101
	v_mov_b32_e32 v139, v109
	v_mul_f32_e32 v134, 0x3d93cd3a, v134
	v_pk_mul_f32 v[138:139], v[138:139], v[172:173]
	v_cvt_pk_bf16_f32 v134, v137, v134
	v_mul_f32_e32 v135, 0x3d93cd3a, v135
	v_add_f32_e32 v137, v138, v139
	global_store_dwordx2 v[132:133], v[146:147], off offset:288
	v_mul_f32_e32 v137, 0x3d93cd3a, v137
	v_cvt_pk_bf16_f32 v135, v135, v137
	global_store_dwordx2 v[132:133], v[134:135], off offset:352
	v_add_u32_e32 v132, s22, v211
	v_ashrrev_i32_e32 v133, 31, v132
	v_lshlrev_b64 v[134:135], 8, v[132:133]
	v_ashrrev_i32_e32 v133, 11, v132
	v_and_b32_e32 v133, -8, v133
	v_add_u32_e32 v138, v133, v131
	v_ashrrev_i32_e32 v139, 31, v138
	v_lshlrev_b64 v[138:139], 14, v[138:139]
	s_movk_i32 s18, 0x3faf
	v_and_or_b32 v132, v132, s18, v138
	v_lshl_add_u64 v[134:135], v[194:195], 0, v[134:135]
	v_mad_u64_u32 v[132:133], s[18:19], v132, s2, v[196:197]
	v_mad_i32_i24 v133, v139, s2, v133
	global_load_dwordx4 v[158:161], v[134:135], off
	global_load_dwordx4 v[162:165], v[134:135], off offset:16
	global_load_dwordx4 v[166:169], v[134:135], off offset:128
	global_load_dwordx4 v[170:173], v[134:135], off offset:144
	v_mov_b32_e32 v142, v94
	v_mov_b32_e32 v143, v86
	v_mov_b32_e32 v148, v96
	v_mov_b32_e32 v149, v88
	s_waitcnt vmcnt(3)
	v_pk_mul_f32 v[142:143], v[142:143], v[158:159]
	s_nop 0
	v_sub_f32_e32 v137, v142, v143
	v_mov_b32_e32 v142, v95
	v_mov_b32_e32 v143, v87
	v_pk_mul_f32 v[142:143], v[142:143], v[160:161]
	v_mul_f32_e32 v137, 0x3d93cd3a, v137
	v_sub_f32_e32 v142, v142, v143
	v_mul_f32_e32 v142, 0x3d93cd3a, v142
	v_cvt_pk_bf16_f32 v146, v137, v142
	s_waitcnt vmcnt(2)
	v_pk_mul_f32 v[148:149], v[148:149], v[162:163]
	s_nop 0
	v_sub_f32_e32 v137, v148, v149
	v_mov_b32_e32 v148, v97
	v_mov_b32_e32 v149, v89
	v_pk_mul_f32 v[148:149], v[148:149], v[164:165]
	v_mul_f32_e32 v137, 0x3d93cd3a, v137
	v_sub_f32_e32 v147, v148, v149
	v_mul_f32_e32 v147, 0x3d93cd3a, v147
	v_cvt_pk_bf16_f32 v147, v137, v147
	global_store_dwordx2 v[132:133], v[146:147], off offset:256
	v_mov_b32_e32 v146, v86
	v_mov_b32_e32 v147, v94
	v_pk_mul_f32 v[138:139], v[146:147], v[158:159]
	s_nop 0
	v_add_f32_e32 v137, v138, v139
	v_mov_b32_e32 v138, v87
	v_mov_b32_e32 v139, v95
	v_pk_mul_f32 v[138:139], v[138:139], v[160:161]
	v_mov_b32_e32 v140, v88
	v_add_f32_e32 v138, v138, v139
	v_mov_b32_e32 v141, v96
	v_mul_f32_e32 v137, 0x3d93cd3a, v137
	v_mul_f32_e32 v138, 0x3d93cd3a, v138
	v_pk_mul_f32 v[140:141], v[140:141], v[162:163]
	v_cvt_pk_bf16_f32 v138, v137, v138
	v_mov_b32_e32 v142, v90
	v_add_f32_e32 v137, v140, v141
	v_mov_b32_e32 v140, v89
	v_mov_b32_e32 v141, v97
	v_pk_mul_f32 v[140:141], v[140:141], v[164:165]
	v_mul_f32_e32 v137, 0x3d93cd3a, v137
	v_add_f32_e32 v139, v140, v141
	v_mul_f32_e32 v139, 0x3d93cd3a, v139
	v_cvt_pk_bf16_f32 v139, v137, v139
	global_store_dwordx2 v[132:133], v[138:139], off offset:320
	v_mov_b32_e32 v143, v82
	s_waitcnt vmcnt(3)
	v_pk_mul_f32 v[142:143], v[142:143], v[166:167]
	s_nop 0
	v_sub_f32_e32 v137, v142, v143
	v_mov_b32_e32 v142, v91
	v_mov_b32_e32 v143, v83
	v_pk_mul_f32 v[142:143], v[142:143], v[168:169]
	v_mul_f32_e32 v137, 0x3d93cd3a, v137
	v_sub_f32_e32 v142, v142, v143
	v_mul_f32_e32 v142, 0x3d93cd3a, v142
	v_cvt_pk_bf16_f32 v146, v137, v142
	v_mov_b32_e32 v134, v92
	v_mov_b32_e32 v135, v84
	s_waitcnt vmcnt(2)
	v_pk_mul_f32 v[134:135], v[134:135], v[170:171]
	s_nop 0
	v_sub_f32_e32 v134, v134, v135
	v_mul_f32_e32 v137, 0x3d93cd3a, v134
	v_mov_b32_e32 v134, v93
	v_mov_b32_e32 v135, v85
	v_pk_mul_f32 v[134:135], v[134:135], v[172:173]
	s_nop 0
	v_sub_f32_e32 v134, v134, v135
	v_mul_f32_e32 v134, 0x3d93cd3a, v134
	v_cvt_pk_bf16_f32 v147, v137, v134
	v_mov_b32_e32 v134, v82
	v_mov_b32_e32 v135, v90
	v_pk_mul_f32 v[134:135], v[134:135], v[166:167]
	v_mov_b32_e32 v138, v84
	v_add_f32_e32 v134, v134, v135
	v_mul_f32_e32 v137, 0x3d93cd3a, v134
	v_mov_b32_e32 v134, v83
	v_mov_b32_e32 v135, v91
	v_mov_b32_e32 v139, v92
	v_pk_mul_f32 v[134:135], v[134:135], v[168:169]
	v_pk_mul_f32 v[138:139], v[138:139], v[170:171]
	v_add_f32_e32 v134, v134, v135
	v_add_f32_e32 v135, v138, v139
	v_mov_b32_e32 v138, v85
	v_mov_b32_e32 v139, v93
	v_mul_f32_e32 v134, 0x3d93cd3a, v134
	v_pk_mul_f32 v[138:139], v[138:139], v[172:173]
	v_cvt_pk_bf16_f32 v134, v137, v134
	v_mul_f32_e32 v135, 0x3d93cd3a, v135
	v_add_f32_e32 v137, v138, v139
	global_store_dwordx2 v[132:133], v[146:147], off offset:288
	v_mul_f32_e32 v137, 0x3d93cd3a, v137
	v_cvt_pk_bf16_f32 v135, v135, v137
	global_store_dwordx2 v[132:133], v[134:135], off offset:352
	v_add_u32_e32 v132, s22, v212
	v_ashrrev_i32_e32 v133, 31, v132
	v_lshlrev_b64 v[134:135], 8, v[132:133]
	v_ashrrev_i32_e32 v133, 11, v132
	v_and_b32_e32 v133, -8, v133
	v_add_u32_e32 v138, v133, v131
	v_ashrrev_i32_e32 v139, 31, v138
	v_lshlrev_b64 v[138:139], 14, v[138:139]
	s_movk_i32 s18, 0x3fbf
	v_and_or_b32 v132, v132, s18, v138
	v_lshl_add_u64 v[134:135], v[194:195], 0, v[134:135]
	v_mad_u64_u32 v[132:133], s[18:19], v132, s2, v[196:197]
	v_mad_i32_i24 v133, v139, s2, v133
	global_load_dwordx4 v[158:161], v[134:135], off
	global_load_dwordx4 v[162:165], v[134:135], off offset:16
	global_load_dwordx4 v[166:169], v[134:135], off offset:128
	global_load_dwordx4 v[170:173], v[134:135], off offset:144
	v_mov_b32_e32 v142, v78
	v_mov_b32_e32 v143, v70
	v_mov_b32_e32 v148, v80
	v_mov_b32_e32 v149, v72
	s_waitcnt vmcnt(3)
	v_pk_mul_f32 v[142:143], v[142:143], v[158:159]
	s_nop 0
	v_sub_f32_e32 v137, v142, v143
	v_mov_b32_e32 v142, v79
	v_mov_b32_e32 v143, v71
	v_pk_mul_f32 v[142:143], v[142:143], v[160:161]
	v_mul_f32_e32 v137, 0x3d93cd3a, v137
	v_sub_f32_e32 v142, v142, v143
	v_mul_f32_e32 v142, 0x3d93cd3a, v142
	v_cvt_pk_bf16_f32 v146, v137, v142
	s_waitcnt vmcnt(2)
	v_pk_mul_f32 v[148:149], v[148:149], v[162:163]
	s_nop 0
	v_sub_f32_e32 v137, v148, v149
	v_mov_b32_e32 v148, v81
	v_mov_b32_e32 v149, v73
	v_pk_mul_f32 v[148:149], v[148:149], v[164:165]
	v_mul_f32_e32 v137, 0x3d93cd3a, v137
	v_sub_f32_e32 v147, v148, v149
	v_mul_f32_e32 v147, 0x3d93cd3a, v147
	v_cvt_pk_bf16_f32 v147, v137, v147
	global_store_dwordx2 v[132:133], v[146:147], off offset:256
	v_mov_b32_e32 v146, v70
	v_mov_b32_e32 v147, v78
	v_pk_mul_f32 v[138:139], v[146:147], v[158:159]
	s_nop 0
	v_add_f32_e32 v137, v138, v139
	v_mov_b32_e32 v138, v71
	v_mov_b32_e32 v139, v79
	v_pk_mul_f32 v[138:139], v[138:139], v[160:161]
	v_mov_b32_e32 v140, v72
	v_add_f32_e32 v138, v138, v139
	v_mov_b32_e32 v141, v80
	v_mul_f32_e32 v137, 0x3d93cd3a, v137
	v_mul_f32_e32 v138, 0x3d93cd3a, v138
	v_pk_mul_f32 v[140:141], v[140:141], v[162:163]
	v_cvt_pk_bf16_f32 v138, v137, v138
	v_mov_b32_e32 v142, v74
	v_add_f32_e32 v137, v140, v141
	v_mov_b32_e32 v140, v73
	v_mov_b32_e32 v141, v81
	v_pk_mul_f32 v[140:141], v[140:141], v[164:165]
	v_mul_f32_e32 v137, 0x3d93cd3a, v137
	v_add_f32_e32 v139, v140, v141
	v_mul_f32_e32 v139, 0x3d93cd3a, v139
	v_cvt_pk_bf16_f32 v139, v137, v139
	global_store_dwordx2 v[132:133], v[138:139], off offset:320
	v_mov_b32_e32 v143, v66
	s_waitcnt vmcnt(3)
	v_pk_mul_f32 v[142:143], v[142:143], v[166:167]
	s_nop 0
	v_sub_f32_e32 v137, v142, v143
	v_mov_b32_e32 v142, v75
	v_mov_b32_e32 v143, v67
	v_pk_mul_f32 v[142:143], v[142:143], v[168:169]
	v_mul_f32_e32 v137, 0x3d93cd3a, v137
	v_sub_f32_e32 v142, v142, v143
	v_mul_f32_e32 v142, 0x3d93cd3a, v142
	v_cvt_pk_bf16_f32 v146, v137, v142
	v_mov_b32_e32 v134, v76
	v_mov_b32_e32 v135, v68
	s_waitcnt vmcnt(2)
	v_pk_mul_f32 v[134:135], v[134:135], v[170:171]
	s_nop 0
	v_sub_f32_e32 v134, v134, v135
	v_mul_f32_e32 v137, 0x3d93cd3a, v134
	v_mov_b32_e32 v134, v77
	v_mov_b32_e32 v135, v69
	v_pk_mul_f32 v[134:135], v[134:135], v[172:173]
	s_nop 0
	v_sub_f32_e32 v134, v134, v135
	v_mul_f32_e32 v134, 0x3d93cd3a, v134
	v_cvt_pk_bf16_f32 v147, v137, v134
	v_mov_b32_e32 v134, v66
	v_mov_b32_e32 v135, v74
	v_pk_mul_f32 v[134:135], v[134:135], v[166:167]
	v_mov_b32_e32 v138, v68
	v_add_f32_e32 v134, v134, v135
	v_mul_f32_e32 v137, 0x3d93cd3a, v134
	v_mov_b32_e32 v134, v67
	v_mov_b32_e32 v135, v75
	v_mov_b32_e32 v139, v76
	v_pk_mul_f32 v[134:135], v[134:135], v[168:169]
	v_pk_mul_f32 v[138:139], v[138:139], v[170:171]
	v_add_f32_e32 v134, v134, v135
	v_add_f32_e32 v135, v138, v139
	v_mov_b32_e32 v138, v69
	v_mov_b32_e32 v139, v77
	v_mul_f32_e32 v134, 0x3d93cd3a, v134
	v_pk_mul_f32 v[138:139], v[138:139], v[172:173]
	v_cvt_pk_bf16_f32 v134, v137, v134
	v_mul_f32_e32 v135, 0x3d93cd3a, v135
	v_add_f32_e32 v137, v138, v139
	global_store_dwordx2 v[132:133], v[146:147], off offset:288
	v_mul_f32_e32 v137, 0x3d93cd3a, v137
	v_cvt_pk_bf16_f32 v135, v135, v137
	global_store_dwordx2 v[132:133], v[134:135], off offset:352
	v_add_u32_e32 v132, s22, v213
	v_ashrrev_i32_e32 v133, 31, v132
	v_lshlrev_b64 v[134:135], 8, v[132:133]
	v_ashrrev_i32_e32 v133, 11, v132
	v_and_b32_e32 v133, -8, v133
	v_add_u32_e32 v138, v133, v131
	v_ashrrev_i32_e32 v139, 31, v138
	v_lshlrev_b64 v[138:139], 14, v[138:139]
	s_movk_i32 s18, 0x3fcf
	v_and_or_b32 v132, v132, s18, v138
	v_lshl_add_u64 v[134:135], v[194:195], 0, v[134:135]
	v_mad_u64_u32 v[132:133], s[18:19], v132, s2, v[196:197]
	v_mad_i32_i24 v133, v139, s2, v133
	global_load_dwordx4 v[158:161], v[134:135], off
	global_load_dwordx4 v[162:165], v[134:135], off offset:16
	global_load_dwordx4 v[166:169], v[134:135], off offset:128
	global_load_dwordx4 v[170:173], v[134:135], off offset:144
	v_mov_b32_e32 v142, v62
	v_mov_b32_e32 v143, v54
	v_mov_b32_e32 v148, v64
	v_mov_b32_e32 v149, v56
	s_waitcnt vmcnt(3)
	v_pk_mul_f32 v[142:143], v[142:143], v[158:159]
	s_nop 0
	v_sub_f32_e32 v137, v142, v143
	v_mov_b32_e32 v142, v63
	v_mov_b32_e32 v143, v55
	v_pk_mul_f32 v[142:143], v[142:143], v[160:161]
	v_mul_f32_e32 v137, 0x3d93cd3a, v137
	v_sub_f32_e32 v142, v142, v143
	v_mul_f32_e32 v142, 0x3d93cd3a, v142
	v_cvt_pk_bf16_f32 v146, v137, v142
	s_waitcnt vmcnt(2)
	v_pk_mul_f32 v[148:149], v[148:149], v[162:163]
	s_nop 0
	v_sub_f32_e32 v137, v148, v149
	v_mov_b32_e32 v148, v65
	v_mov_b32_e32 v149, v57
	v_pk_mul_f32 v[148:149], v[148:149], v[164:165]
	v_mul_f32_e32 v137, 0x3d93cd3a, v137
	v_sub_f32_e32 v147, v148, v149
	v_mul_f32_e32 v147, 0x3d93cd3a, v147
	v_cvt_pk_bf16_f32 v147, v137, v147
	global_store_dwordx2 v[132:133], v[146:147], off offset:256
	v_mov_b32_e32 v146, v54
	v_mov_b32_e32 v147, v62
	v_pk_mul_f32 v[138:139], v[146:147], v[158:159]
	s_nop 0
	v_add_f32_e32 v137, v138, v139
	v_mov_b32_e32 v138, v55
	v_mov_b32_e32 v139, v63
	v_pk_mul_f32 v[138:139], v[138:139], v[160:161]
	v_mov_b32_e32 v140, v56
	v_add_f32_e32 v138, v138, v139
	v_mov_b32_e32 v141, v64
	v_mul_f32_e32 v137, 0x3d93cd3a, v137
	v_mul_f32_e32 v138, 0x3d93cd3a, v138
	v_pk_mul_f32 v[140:141], v[140:141], v[162:163]
	v_cvt_pk_bf16_f32 v138, v137, v138
	v_mov_b32_e32 v142, v58
	v_add_f32_e32 v137, v140, v141
	v_mov_b32_e32 v140, v57
	v_mov_b32_e32 v141, v65
	v_pk_mul_f32 v[140:141], v[140:141], v[164:165]
	v_mul_f32_e32 v137, 0x3d93cd3a, v137
	v_add_f32_e32 v139, v140, v141
	v_mul_f32_e32 v139, 0x3d93cd3a, v139
	v_cvt_pk_bf16_f32 v139, v137, v139
	global_store_dwordx2 v[132:133], v[138:139], off offset:320
	v_mov_b32_e32 v143, v50
	s_waitcnt vmcnt(3)
	v_pk_mul_f32 v[142:143], v[142:143], v[166:167]
	s_nop 0
	v_sub_f32_e32 v137, v142, v143
	v_mov_b32_e32 v142, v59
	v_mov_b32_e32 v143, v51
	v_pk_mul_f32 v[142:143], v[142:143], v[168:169]
	v_mul_f32_e32 v137, 0x3d93cd3a, v137
	v_sub_f32_e32 v142, v142, v143
	v_mul_f32_e32 v142, 0x3d93cd3a, v142
	v_cvt_pk_bf16_f32 v146, v137, v142
	v_mov_b32_e32 v134, v60
	v_mov_b32_e32 v135, v52
	s_waitcnt vmcnt(2)
	v_pk_mul_f32 v[134:135], v[134:135], v[170:171]
	s_nop 0
	v_sub_f32_e32 v134, v134, v135
	v_mul_f32_e32 v137, 0x3d93cd3a, v134
	v_mov_b32_e32 v134, v61
	v_mov_b32_e32 v135, v53
	v_pk_mul_f32 v[134:135], v[134:135], v[172:173]
	s_nop 0
	v_sub_f32_e32 v134, v134, v135
	v_mul_f32_e32 v134, 0x3d93cd3a, v134
	v_cvt_pk_bf16_f32 v147, v137, v134
	v_mov_b32_e32 v134, v50
	v_mov_b32_e32 v135, v58
	v_pk_mul_f32 v[134:135], v[134:135], v[166:167]
	v_mov_b32_e32 v138, v52
	v_add_f32_e32 v134, v134, v135
	v_mul_f32_e32 v137, 0x3d93cd3a, v134
	v_mov_b32_e32 v134, v51
	v_mov_b32_e32 v135, v59
	v_mov_b32_e32 v139, v60
	v_pk_mul_f32 v[134:135], v[134:135], v[168:169]
	v_pk_mul_f32 v[138:139], v[138:139], v[170:171]
	v_add_f32_e32 v134, v134, v135
	v_add_f32_e32 v135, v138, v139
	v_mov_b32_e32 v138, v53
	v_mov_b32_e32 v139, v61
	v_mul_f32_e32 v134, 0x3d93cd3a, v134
	v_pk_mul_f32 v[138:139], v[138:139], v[172:173]
	v_cvt_pk_bf16_f32 v134, v137, v134
	v_mul_f32_e32 v135, 0x3d93cd3a, v135
	v_add_f32_e32 v137, v138, v139
	global_store_dwordx2 v[132:133], v[146:147], off offset:288
	v_mul_f32_e32 v137, 0x3d93cd3a, v137
	v_cvt_pk_bf16_f32 v135, v135, v137
	global_store_dwordx2 v[132:133], v[134:135], off offset:352
	v_add_u32_e32 v132, s22, v214
	v_ashrrev_i32_e32 v133, 31, v132
	v_lshlrev_b64 v[134:135], 8, v[132:133]
	v_ashrrev_i32_e32 v133, 11, v132
	v_and_b32_e32 v133, -8, v133
	v_add_u32_e32 v138, v133, v131
	v_ashrrev_i32_e32 v139, 31, v138
	v_lshlrev_b64 v[138:139], 14, v[138:139]
	s_movk_i32 s18, 0x3fdf
	v_and_or_b32 v132, v132, s18, v138
	v_lshl_add_u64 v[134:135], v[194:195], 0, v[134:135]
	v_mad_u64_u32 v[132:133], s[18:19], v132, s2, v[196:197]
	v_mad_i32_i24 v133, v139, s2, v133
	global_load_dwordx4 v[158:161], v[134:135], off
	global_load_dwordx4 v[162:165], v[134:135], off offset:16
	global_load_dwordx4 v[166:169], v[134:135], off offset:128
	global_load_dwordx4 v[170:173], v[134:135], off offset:144
	v_mov_b32_e32 v142, v46
	v_mov_b32_e32 v143, v38
	v_mov_b32_e32 v148, v48
	v_mov_b32_e32 v149, v40
	s_waitcnt vmcnt(3)
	v_pk_mul_f32 v[142:143], v[142:143], v[158:159]
	s_nop 0
	v_sub_f32_e32 v137, v142, v143
	v_mov_b32_e32 v142, v47
	v_mov_b32_e32 v143, v39
	v_pk_mul_f32 v[142:143], v[142:143], v[160:161]
	v_mul_f32_e32 v137, 0x3d93cd3a, v137
	v_sub_f32_e32 v142, v142, v143
	v_mul_f32_e32 v142, 0x3d93cd3a, v142
	v_cvt_pk_bf16_f32 v146, v137, v142
	s_waitcnt vmcnt(2)
	v_pk_mul_f32 v[148:149], v[148:149], v[162:163]
	s_nop 0
	v_sub_f32_e32 v137, v148, v149
	v_mov_b32_e32 v148, v49
	v_mov_b32_e32 v149, v41
	v_pk_mul_f32 v[148:149], v[148:149], v[164:165]
	v_mul_f32_e32 v137, 0x3d93cd3a, v137
	v_sub_f32_e32 v147, v148, v149
	v_mul_f32_e32 v147, 0x3d93cd3a, v147
	v_cvt_pk_bf16_f32 v147, v137, v147
	global_store_dwordx2 v[132:133], v[146:147], off offset:256
	v_mov_b32_e32 v146, v38
	v_mov_b32_e32 v147, v46
	v_pk_mul_f32 v[138:139], v[146:147], v[158:159]
	s_nop 0
	v_add_f32_e32 v137, v138, v139
	v_mov_b32_e32 v138, v39
	v_mov_b32_e32 v139, v47
	v_pk_mul_f32 v[138:139], v[138:139], v[160:161]
	v_mov_b32_e32 v140, v40
	v_add_f32_e32 v138, v138, v139
	v_mov_b32_e32 v141, v48
	v_mul_f32_e32 v137, 0x3d93cd3a, v137
	v_mul_f32_e32 v138, 0x3d93cd3a, v138
	v_pk_mul_f32 v[140:141], v[140:141], v[162:163]
	v_cvt_pk_bf16_f32 v138, v137, v138
	v_mov_b32_e32 v142, v42
	v_add_f32_e32 v137, v140, v141
	v_mov_b32_e32 v140, v41
	v_mov_b32_e32 v141, v49
	v_pk_mul_f32 v[140:141], v[140:141], v[164:165]
	v_mul_f32_e32 v137, 0x3d93cd3a, v137
	v_add_f32_e32 v139, v140, v141
	v_mul_f32_e32 v139, 0x3d93cd3a, v139
	v_cvt_pk_bf16_f32 v139, v137, v139
	global_store_dwordx2 v[132:133], v[138:139], off offset:320
	v_mov_b32_e32 v143, v34
	s_waitcnt vmcnt(3)
	v_pk_mul_f32 v[142:143], v[142:143], v[166:167]
	s_nop 0
	v_sub_f32_e32 v137, v142, v143
	v_mov_b32_e32 v142, v43
	v_mov_b32_e32 v143, v35
	v_pk_mul_f32 v[142:143], v[142:143], v[168:169]
	v_mul_f32_e32 v137, 0x3d93cd3a, v137
	v_sub_f32_e32 v142, v142, v143
	v_mul_f32_e32 v142, 0x3d93cd3a, v142
	v_cvt_pk_bf16_f32 v146, v137, v142
	v_mov_b32_e32 v134, v44
	v_mov_b32_e32 v135, v36
	s_waitcnt vmcnt(2)
	v_pk_mul_f32 v[134:135], v[134:135], v[170:171]
	s_nop 0
	v_sub_f32_e32 v134, v134, v135
	v_mul_f32_e32 v137, 0x3d93cd3a, v134
	v_mov_b32_e32 v134, v45
	v_mov_b32_e32 v135, v37
	v_pk_mul_f32 v[134:135], v[134:135], v[172:173]
	s_nop 0
	v_sub_f32_e32 v134, v134, v135
	v_mul_f32_e32 v134, 0x3d93cd3a, v134
	v_cvt_pk_bf16_f32 v147, v137, v134
	v_mov_b32_e32 v134, v34
	v_mov_b32_e32 v135, v42
	v_pk_mul_f32 v[134:135], v[134:135], v[166:167]
	v_mov_b32_e32 v138, v36
	v_add_f32_e32 v134, v134, v135
	v_mul_f32_e32 v137, 0x3d93cd3a, v134
	v_mov_b32_e32 v134, v35
	v_mov_b32_e32 v135, v43
	v_mov_b32_e32 v139, v44
	v_pk_mul_f32 v[134:135], v[134:135], v[168:169]
	v_pk_mul_f32 v[138:139], v[138:139], v[170:171]
	v_add_f32_e32 v134, v134, v135
	v_add_f32_e32 v135, v138, v139
	v_mov_b32_e32 v138, v37
	v_mov_b32_e32 v139, v45
	v_mul_f32_e32 v134, 0x3d93cd3a, v134
	v_pk_mul_f32 v[138:139], v[138:139], v[172:173]
	v_cvt_pk_bf16_f32 v134, v137, v134
	v_mul_f32_e32 v135, 0x3d93cd3a, v135
	v_add_f32_e32 v137, v138, v139
	global_store_dwordx2 v[132:133], v[146:147], off offset:288
	v_mul_f32_e32 v137, 0x3d93cd3a, v137
	v_cvt_pk_bf16_f32 v135, v135, v137
	global_store_dwordx2 v[132:133], v[134:135], off offset:352
	v_add_u32_e32 v132, s22, v215
	v_ashrrev_i32_e32 v133, 31, v132
	v_lshlrev_b64 v[134:135], 8, v[132:133]
	v_ashrrev_i32_e32 v133, 11, v132
	v_and_b32_e32 v133, -8, v133
	v_add_u32_e32 v138, v133, v131
	v_ashrrev_i32_e32 v139, 31, v138
	v_lshlrev_b64 v[138:139], 14, v[138:139]
	s_movk_i32 s18, 0x3fef
	v_and_or_b32 v132, v132, s18, v138
	v_lshl_add_u64 v[134:135], v[194:195], 0, v[134:135]
	v_mad_u64_u32 v[132:133], s[18:19], v132, s2, v[196:197]
	v_mad_i32_i24 v133, v139, s2, v133
	global_load_dwordx4 v[158:161], v[134:135], off
	global_load_dwordx4 v[162:165], v[134:135], off offset:16
	global_load_dwordx4 v[166:169], v[134:135], off offset:128
	global_load_dwordx4 v[170:173], v[134:135], off offset:144
	v_mov_b32_e32 v142, v30
	v_mov_b32_e32 v143, v22
	v_mov_b32_e32 v148, v32
	v_mov_b32_e32 v149, v24
	s_waitcnt vmcnt(3)
	v_pk_mul_f32 v[142:143], v[142:143], v[158:159]
	s_nop 0
	v_sub_f32_e32 v137, v142, v143
	v_mov_b32_e32 v142, v31
	v_mov_b32_e32 v143, v23
	v_pk_mul_f32 v[142:143], v[142:143], v[160:161]
	v_mul_f32_e32 v137, 0x3d93cd3a, v137
	v_sub_f32_e32 v142, v142, v143
	v_mul_f32_e32 v142, 0x3d93cd3a, v142
	v_cvt_pk_bf16_f32 v146, v137, v142
	s_waitcnt vmcnt(2)
	v_pk_mul_f32 v[148:149], v[148:149], v[162:163]
	s_nop 0
	v_sub_f32_e32 v137, v148, v149
	v_mov_b32_e32 v148, v33
	v_mov_b32_e32 v149, v25
	v_pk_mul_f32 v[148:149], v[148:149], v[164:165]
	v_mul_f32_e32 v137, 0x3d93cd3a, v137
	v_sub_f32_e32 v147, v148, v149
	v_mul_f32_e32 v147, 0x3d93cd3a, v147
	v_cvt_pk_bf16_f32 v147, v137, v147
	global_store_dwordx2 v[132:133], v[146:147], off offset:256
	v_mov_b32_e32 v146, v22
	v_mov_b32_e32 v147, v30
	v_pk_mul_f32 v[138:139], v[146:147], v[158:159]
	s_nop 0
	v_add_f32_e32 v137, v138, v139
	v_mov_b32_e32 v138, v23
	v_mov_b32_e32 v139, v31
	v_pk_mul_f32 v[138:139], v[138:139], v[160:161]
	v_mov_b32_e32 v140, v24
	v_add_f32_e32 v138, v138, v139
	v_mov_b32_e32 v141, v32
	v_mul_f32_e32 v137, 0x3d93cd3a, v137
	v_mul_f32_e32 v138, 0x3d93cd3a, v138
	v_pk_mul_f32 v[140:141], v[140:141], v[162:163]
	v_cvt_pk_bf16_f32 v138, v137, v138
	v_mov_b32_e32 v142, v26
	v_add_f32_e32 v137, v140, v141
	v_mov_b32_e32 v140, v25
	v_mov_b32_e32 v141, v33
	v_pk_mul_f32 v[140:141], v[140:141], v[164:165]
	v_mul_f32_e32 v137, 0x3d93cd3a, v137
	v_add_f32_e32 v139, v140, v141
	v_mul_f32_e32 v139, 0x3d93cd3a, v139
	v_cvt_pk_bf16_f32 v139, v137, v139
	global_store_dwordx2 v[132:133], v[138:139], off offset:320
	v_mov_b32_e32 v143, v18
	s_waitcnt vmcnt(3)
	v_pk_mul_f32 v[142:143], v[142:143], v[166:167]
	s_nop 0
	v_sub_f32_e32 v137, v142, v143
	v_mov_b32_e32 v142, v27
	v_mov_b32_e32 v143, v19
	v_pk_mul_f32 v[142:143], v[142:143], v[168:169]
	v_mul_f32_e32 v137, 0x3d93cd3a, v137
	v_sub_f32_e32 v142, v142, v143
	v_mul_f32_e32 v142, 0x3d93cd3a, v142
	v_cvt_pk_bf16_f32 v146, v137, v142
	v_mov_b32_e32 v134, v28
	v_mov_b32_e32 v135, v20
	s_waitcnt vmcnt(2)
	v_pk_mul_f32 v[134:135], v[134:135], v[170:171]
	s_nop 0
	v_sub_f32_e32 v134, v134, v135
	v_mul_f32_e32 v137, 0x3d93cd3a, v134
	v_mov_b32_e32 v134, v29
	v_mov_b32_e32 v135, v21
	v_pk_mul_f32 v[134:135], v[134:135], v[172:173]
	s_nop 0
	v_sub_f32_e32 v134, v134, v135
	v_mul_f32_e32 v134, 0x3d93cd3a, v134
	v_cvt_pk_bf16_f32 v147, v137, v134
	v_mov_b32_e32 v134, v18
	v_mov_b32_e32 v135, v26
	v_pk_mul_f32 v[134:135], v[134:135], v[166:167]
	v_mov_b32_e32 v138, v20
	v_add_f32_e32 v134, v134, v135
	v_mul_f32_e32 v137, 0x3d93cd3a, v134
	v_mov_b32_e32 v134, v19
	v_mov_b32_e32 v135, v27
	v_mov_b32_e32 v139, v28
	v_pk_mul_f32 v[134:135], v[134:135], v[168:169]
	v_pk_mul_f32 v[138:139], v[138:139], v[170:171]
	v_add_f32_e32 v134, v134, v135
	v_add_f32_e32 v135, v138, v139
	v_mov_b32_e32 v138, v21
	v_mov_b32_e32 v139, v29
	v_mul_f32_e32 v134, 0x3d93cd3a, v134
	v_pk_mul_f32 v[138:139], v[138:139], v[172:173]
	v_cvt_pk_bf16_f32 v134, v137, v134
	v_mul_f32_e32 v135, 0x3d93cd3a, v135
	v_add_f32_e32 v137, v138, v139
	global_store_dwordx2 v[132:133], v[146:147], off offset:288
	v_mul_f32_e32 v137, 0x3d93cd3a, v137
	v_cvt_pk_bf16_f32 v135, v135, v137
	global_store_dwordx2 v[132:133], v[134:135], off offset:352
	v_add_u32_e32 v132, s22, v216
	v_ashrrev_i32_e32 v133, 31, v132
	v_lshlrev_b64 v[134:135], 8, v[132:133]
	v_ashrrev_i32_e32 v133, 11, v132
	v_and_b32_e32 v133, -8, v133
	v_add_u32_e32 v138, v133, v131
	v_ashrrev_i32_e32 v139, 31, v138
	v_lshlrev_b64 v[138:139], 14, v[138:139]
	s_movk_i32 s18, 0x3fff
	v_and_or_b32 v131, v132, s18, v138
	v_lshl_add_u64 v[134:135], v[194:195], 0, v[134:135]
	v_mad_u64_u32 v[132:133], s[18:19], v131, s2, v[196:197]
	v_mad_i32_i24 v133, v139, s2, v133
	global_load_dwordx4 v[158:161], v[134:135], off
	global_load_dwordx4 v[162:165], v[134:135], off offset:16
	global_load_dwordx4 v[166:169], v[134:135], off offset:128
	global_load_dwordx4 v[170:173], v[134:135], off offset:144
	v_mov_b32_e32 v142, v14
	v_mov_b32_e32 v143, v6
	v_mov_b32_e32 v148, v16
	v_mov_b32_e32 v149, v8
	s_waitcnt vmcnt(3)
	v_pk_mul_f32 v[142:143], v[142:143], v[158:159]
	s_nop 0
	v_sub_f32_e32 v131, v142, v143
	v_mov_b32_e32 v142, v15
	v_mov_b32_e32 v143, v7
	v_pk_mul_f32 v[142:143], v[142:143], v[160:161]
	v_mul_f32_e32 v131, 0x3d93cd3a, v131
	v_sub_f32_e32 v137, v142, v143
	v_mul_f32_e32 v137, 0x3d93cd3a, v137
	v_cvt_pk_bf16_f32 v146, v131, v137
	s_waitcnt vmcnt(2)
	v_pk_mul_f32 v[148:149], v[148:149], v[162:163]
	s_nop 0
	v_sub_f32_e32 v131, v148, v149
	v_mov_b32_e32 v148, v17
	v_mov_b32_e32 v149, v9
	v_pk_mul_f32 v[148:149], v[148:149], v[164:165]
	v_mul_f32_e32 v131, 0x3d93cd3a, v131
	v_sub_f32_e32 v137, v148, v149
	v_mul_f32_e32 v137, 0x3d93cd3a, v137
	v_cvt_pk_bf16_f32 v147, v131, v137
	global_store_dwordx2 v[132:133], v[146:147], off offset:256
	v_mov_b32_e32 v146, v6
	v_mov_b32_e32 v147, v14
	v_pk_mul_f32 v[138:139], v[146:147], v[158:159]
	s_nop 0
	v_add_f32_e32 v131, v138, v139
	v_mov_b32_e32 v138, v7
	v_mov_b32_e32 v139, v15
	v_pk_mul_f32 v[138:139], v[138:139], v[160:161]
	v_mov_b32_e32 v140, v8
	v_mov_b32_e32 v141, v16
	v_mul_f32_e32 v131, 0x3d93cd3a, v131
	v_add_f32_e32 v137, v138, v139
	v_pk_mul_f32 v[140:141], v[140:141], v[162:163]
	v_mul_f32_e32 v137, 0x3d93cd3a, v137
	v_cvt_pk_bf16_f32 v138, v131, v137
	v_add_f32_e32 v131, v140, v141
	v_mov_b32_e32 v140, v9
	v_mov_b32_e32 v141, v17
	v_pk_mul_f32 v[140:141], v[140:141], v[164:165]
	v_mul_f32_e32 v131, 0x3d93cd3a, v131
	v_add_f32_e32 v137, v140, v141
	v_mul_f32_e32 v137, 0x3d93cd3a, v137
	v_cvt_pk_bf16_f32 v139, v131, v137
	global_store_dwordx2 v[132:133], v[138:139], off offset:320
	v_mov_b32_e32 v142, v10
	v_mov_b32_e32 v143, v2
	s_waitcnt vmcnt(3)
	v_pk_mul_f32 v[142:143], v[142:143], v[166:167]
	s_nop 0
	v_sub_f32_e32 v131, v142, v143
	v_mov_b32_e32 v142, v11
	v_mov_b32_e32 v143, v3
	v_pk_mul_f32 v[142:143], v[142:143], v[168:169]
	v_mul_f32_e32 v131, 0x3d93cd3a, v131
	v_sub_f32_e32 v137, v142, v143
	v_mov_b32_e32 v134, v12
	v_mov_b32_e32 v135, v4
	v_mul_f32_e32 v137, 0x3d93cd3a, v137
	v_cvt_pk_bf16_f32 v146, v131, v137
	s_waitcnt vmcnt(2)
	v_pk_mul_f32 v[134:135], v[134:135], v[170:171]
	s_nop 0
	v_sub_f32_e32 v131, v134, v135
	v_mov_b32_e32 v134, v13
	v_mov_b32_e32 v135, v5
	v_pk_mul_f32 v[134:135], v[134:135], v[172:173]
	v_mul_f32_e32 v131, 0x3d93cd3a, v131
	v_sub_f32_e32 v134, v134, v135
	v_mul_f32_e32 v134, 0x3d93cd3a, v134
	v_cvt_pk_bf16_f32 v147, v131, v134
	v_mov_b32_e32 v134, v2
	v_mov_b32_e32 v135, v10
	v_pk_mul_f32 v[134:135], v[134:135], v[166:167]
	v_mov_b32_e32 v138, v4
	v_add_f32_e32 v131, v134, v135
	v_mov_b32_e32 v134, v3
	v_mov_b32_e32 v135, v11
	v_pk_mul_f32 v[134:135], v[134:135], v[168:169]
	v_mov_b32_e32 v139, v12
	v_add_f32_e32 v134, v134, v135
	v_mul_f32_e32 v131, 0x3d93cd3a, v131
	v_mul_f32_e32 v134, 0x3d93cd3a, v134
	v_pk_mul_f32 v[138:139], v[138:139], v[170:171]
	v_cvt_pk_bf16_f32 v134, v131, v134
	global_store_dwordx2 v[132:133], v[146:147], off offset:288
	v_add_f32_e32 v131, v138, v139
	v_mov_b32_e32 v138, v5
	v_mov_b32_e32 v139, v13
	v_pk_mul_f32 v[138:139], v[138:139], v[172:173]
	v_mul_f32_e32 v131, 0x3d93cd3a, v131
	v_add_f32_e32 v135, v138, v139
	v_mul_f32_e32 v135, 0x3d93cd3a, v135
	v_cvt_pk_bf16_f32 v135, v131, v135
	global_store_dwordx2 v[132:133], v[134:135], off offset:352
	s_cbranch_execz .LBB0_852
